# invalidate issued before the poll loop in parked counter waits (group seams, scan-states wait, ret_kv wait); P5->P6 seam polls both counters with loads in flight together
# speedup vs baseline: 1.0174x; 1.0022x over previous
.LBB0_469:
	s_waitcnt vmcnt(0)
	v_readlane_b32 s66, v254, 22
	v_readlane_b32 s67, v254, 23
	v_readlane_b32 s72, v255, 2
	v_readlane_b32 s52, v254, 55
	s_and_b64 vcc, exec, s[66:67]
	v_readlane_b32 s70, v255, 10
	v_readlane_b32 s73, v255, 3
	v_readlane_b32 s53, v254, 56
	v_readlane_b32 s42, v254, 50
	s_waitcnt vmcnt(63) expcnt(7) lgkmcnt(15)
	s_barrier
	v_readlane_b32 s43, v254, 51
	s_cbranch_vccnz .LBB0_523
	s_cmp_lg_u32 s98, 0
	s_cbranch_scc0 .Lb3_orig
	s_mov_b64 s[100:101], exec
	s_mov_b64 exec, 1
	v_mov_b32_e32 v0, 0x21004
	ds_read_b32 v1, v0
	v_mov_b32_e32 v0, 0xfa0e000
	s_mov_b32 s99, 0
	s_waitcnt lgkmcnt(0)
	buffer_inv sc1

.Lb3_done:
	s_waitcnt vmcnt(0)
	s_mov_b64 exec, s[100:101]
	s_branch .LBB0_523

.Lp3_noarr:
	s_waitcnt vmcnt(0)
	s_and_b64 vcc, exec, s[66:67]
	s_barrier
	s_cbranch_vccnz .LBB0_592
	s_cmp_lg_u32 s98, 0
	s_cbranch_scc0 .Lb4_orig
	s_mov_b64 s[100:101], exec
	s_mov_b64 exec, 1
	v_mov_b32_e32 v0, 0x21004
	ds_read_b32 v1, v0
	v_mov_b32_e32 v0, 0xfa0e900
	s_mov_b32 s99, 0
	s_waitcnt lgkmcnt(0)
	buffer_inv sc1

.LBB0_697:
	s_waitcnt vmcnt(0)
	s_and_b64 vcc, exec, s[66:67]
	s_barrier
	s_cbranch_vccnz .LBB0_752
	s_cmp_lg_u32 s98, 0
	s_cbranch_scc0 .Lgp_orig_g752
	v_readlane_b32 s99, v255, 10
	s_nop 3
	s_and_b32 s99, s99, 63
	s_lshl_b32 s99, s99, 5
	s_add_i32 s99, s99, 0xfa0f300
	v_mov_b32_e32 v0, s99
	v_mov_b32_e32 v1, 1
	v_mov_b32_e32 v3, 4
	s_mov_b32 s99, 0
	s_mov_b64 s[100:101], exec
	s_mov_b64 exec, 1
	global_atomic_add v0, v1, s[74:75]
	buffer_inv sc1
	v_mov_b32_e32 v4, 0x21004
	ds_read_b32 v5, v4
	v_mov_b32_e32 v4, 0xfa03a00
	s_waitcnt lgkmcnt(0)
.Lgp_poll_g752:
	global_load_dword v2, v0, s[74:75] sc1
	global_load_dword v6, v4, s[74:75] sc1
	s_waitcnt vmcnt(0)
	v_cmp_ge_u32_e32 vcc, v2, v3
	s_cbranch_vccz .Lgp_spin_g752
	v_cmp_ge_u32_e32 vcc, v6, v5
	s_cbranch_vccnz .Lgp_done_g752
.Lgp_spin_g752:
	s_sleep 1
	s_add_i32 s99, s99, 1
	s_cmp_lt_u32 s99, 0x100000
	s_cbranch_scc1 .Lgp_poll_g752

.LBB0_844:
	s_barrier
	s_waitcnt vmcnt(0)
	s_and_b64 vcc, exec, s[66:67]
	s_barrier
	s_cbranch_vccnz .LBB0_898
	s_cmp_lg_u32 s98, 0
	s_cbranch_scc0 .Lgp_orig_g898
	v_readlane_b32 s99, v255, 10
	s_nop 3
	s_and_b32 s99, s99, 63
	s_lshl_b32 s99, s99, 5
	s_add_i32 s99, s99, 0xfa0f300
	v_mov_b32_e32 v0, s99
	v_mov_b32_e32 v1, 1
	v_mov_b32_e32 v3, 8
	s_mov_b32 s99, 0
	s_mov_b64 s[100:101], exec
	s_mov_b64 exec, 1
	global_atomic_add v0, v1, s[74:75]
	buffer_inv sc1

.LBB0_940:
	s_waitcnt vmcnt(0)
	s_and_b64 vcc, exec, s[66:67]
	s_barrier
	s_cbranch_vccnz .LBB0_994
	s_cmp_lg_u32 s98, 0
	s_cbranch_scc0 .Lgp_orig_g994
	v_readlane_b32 s99, v255, 10
	s_nop 3
	s_and_b32 s99, s99, 63
	s_lshl_b32 s99, s99, 5
	s_add_i32 s99, s99, 0xfa0f300
	v_mov_b32_e32 v0, s99
	v_mov_b32_e32 v1, 1
	v_mov_b32_e32 v3, 12
	s_mov_b32 s99, 0
	s_mov_b64 s[100:101], exec
	s_mov_b64 exec, 1
	global_atomic_add v0, v1, s[74:75]
	buffer_inv sc1

.LBB0_1010:
	s_waitcnt vmcnt(0)
	s_and_b64 vcc, exec, s[66:67]
	s_barrier
	s_cbranch_vccnz .LBB0_1064
	s_cmp_lg_u32 s98, 0
	s_cbranch_scc0 .Lgp_orig_g1064
	v_readlane_b32 s99, v255, 10
	s_nop 3
	s_and_b32 s99, s99, 63
	s_lshl_b32 s99, s99, 5
	s_add_i32 s99, s99, 0xfa0f300
	v_mov_b32_e32 v0, s99
	v_mov_b32_e32 v1, 1
	v_mov_b32_e32 v3, 16
	s_mov_b32 s99, 0
	s_mov_b64 s[100:101], exec
	s_mov_b64 exec, 1
	global_atomic_add v0, v1, s[74:75]
	buffer_inv sc1
